# v_c4 + S5 table set-up: the 8 masked reloads of d[] (same address, each followed by vmcnt(0)) replaced by one unmasked load
# speedup vs baseline: 1.0074x; 1.0046x over previous
; __device__ __forceinline__ unsigned f2bf(float f) { unsigned u = __builtin_bit_cast(unsigned, f); return (u + 0x7fffu + ((u >> 16) & 1u)) >> 16; }
; __device__ __forceinline__ unsigned pk2(float lo, float hi) { const f32x2 v = {lo, hi}; const bf16x2_n b = __builtin_convertvector(v, bf16x2_n); return __builtin_bit_cast(unsigned, b); }
; __device__ __forceinline__ f32x4 mfma16(bf16x8 a, bf16x8 b, f32x4 c) { return __builtin_amdgcn_mfma_f32_16x16x32_bf16(a, b, c, 0, 0, 0); }
; __device__ __forceinline__ void s5_phase(LAS unsigned char* lds, const bf16* PROJ, const float* a_re, const float* a_im, const float* b_re, const float* b_im, const float* c_re, const float* c_im, ...
;     ...
;         {   int t_ = tid; asm volatile("" : "+v"(t_)); const int lane = t_ & 63, q4 = lane >> 4, l15 = lane & 15; (void)lane; (void)q4; (void)l15;
;             bf16x8 bfK[4];
; #pragma unroll
;             for (int ks = 0; ks < 4; ++ks) { float v[8];
; #pragma unroll
;                 for (int pp = 0; pp < 4; ++pp) { const f32x2 bb = BB[(16 * ks + 4 * q4 + pp) * 16 + l15]; v[2 * pp] = bb.x; v[2 * pp + 1] = bb.y; }
;                 v4u pk; pk.x = pk2(v[0], v[1]); pk.y = pk2(v[2], v[3]); pk.z = pk2(v[4], v[5]); pk.w = pk2(v[6], v[7]); bfK[ks] = __builtin_bit_cast(bf16x8, pk); asm volatile("" ::: "memory"); }
; #pragma unroll
;             for (int ts = 0; ts < 2; ++ts) { const int tau = ts ? 15 - w : w; f32x4 acc = (f32x4){0.f, 0.f, 0.f, 0.f};
; #pragma unroll
;                 for (int ks = 0; ks < 4; ++ks) { float v[8];
; #pragma unroll
;                     for (int pp = 0; pp < 4; ++pp) { const int p = 16 * ks + 4 * q4 + pp; const f32x2 cc = CC[l15 * 64 + p], pw = POW[tau * 64 + p];
;                         v[2 * pp] = cc.x * pw.x - cc.y * pw.y; v[2 * pp + 1] = -(cc.x * pw.y + cc.y * pw.x); }
;                     v4u pk; pk.x = pk2(v[0], v[1]); pk.y = pk2(v[2], v[3]); pk.z = pk2(v[4], v[5]); pk.w = pk2(v[6], v[7]);
;                     acc = mfma16(__builtin_bit_cast(bf16x8, pk), bfK[ks], acc); asm volatile("" ::: "memory"); }
; #pragma unroll
;                 for (int r = 0; r < 4; ++r) { const int c = 4 * q4 + r; float kv = acc[r]; if (tau == 0 && c == l15) kv += dvec[g * 16 + c];
;                     KTAB[(tau * 16 + c) * 16 + l15] = (unsigned short)f2bf(kv); } }
;         }
.LBB0_1554:
	s_or_b64 exec, exec, s[8:9]
	v_mov_b32_e32 v0, v220
	s_waitcnt lgkmcnt(0)
	s_barrier
	v_readlane_b32 s8, v255, 4
	v_and_b32_e32 v41, 15, v0
	v_lshrrev_b32_e32 v0, 2, v0
	v_and_b32_e32 v0, 12, v0
	v_lshl_add_u32 v40, v41, 3, 0
	v_or_b32_e32 v44, 1, v0
	v_or_b32_e32 v43, 2, v0
	v_lshl_add_u32 v22, v44, 7, v40
	v_lshl_add_u32 v24, v43, 7, v40
	v_or_b32_e32 v42, 3, v0
	v_lshl_add_u32 v45, v0, 7, v40
	ds_read_b64 v[22:23], v22 offset:42496
	ds_read_b64 v[24:25], v24 offset:42496
	ds_read_b64 v[20:21], v45 offset:42496
	v_lshl_add_u32 v26, v42, 7, v40
	ds_read_b64 v[26:27], v26 offset:42496
	s_waitcnt lgkmcnt(2)
	v_cvt_pk_bf16_f32 v34, v24, v25
	v_add_u32_e32 v24, 0xa800, v45
	s_waitcnt lgkmcnt(1)
	v_cvt_pk_bf16_f32 v32, v20, v21
	v_cvt_pk_bf16_f32 v33, v22, v23
	s_waitcnt lgkmcnt(0)
	v_cvt_pk_bf16_f32 v35, v26, v27
	ds_read2_b64 v[20:23], v24 offset0:192 offset1:208
	ds_read2_b64 v[24:27], v24 offset0:224 offset1:240
	s_lshl_b32 s1, s36, 4
	v_cmp_eq_u32_e32 vcc, v0, v41
	s_waitcnt lgkmcnt(1)
	v_cvt_pk_bf16_f32 v28, v20, v21
	s_waitcnt lgkmcnt(0)
	v_cvt_pk_bf16_f32 v30, v24, v25
	v_add_u32_e32 v24, 0xb000, v45
	v_cvt_pk_bf16_f32 v29, v22, v23
	ds_read2_b64 v[20:23], v24 offset0:192 offset1:208
	ds_read2_b64 v[36:39], v24 offset0:224 offset1:240
	v_cvt_pk_bf16_f32 v31, v26, v27
	s_and_b64 s[26:27], s[68:69], vcc
	s_waitcnt lgkmcnt(1)
	v_cvt_pk_bf16_f32 v24, v20, v21
	s_waitcnt lgkmcnt(0)
	v_cvt_pk_bf16_f32 v26, v36, v37
	v_add_u32_e32 v36, 0xb800, v45
	v_cvt_pk_bf16_f32 v25, v22, v23
	v_cvt_pk_bf16_f32 v27, v38, v39
	ds_read2_b64 v[20:23], v36 offset0:192 offset1:208
	ds_read2_b64 v[36:39], v36 offset0:224 offset1:240
	v_lshlrev_b32_e32 v45, 3, v0
	s_waitcnt lgkmcnt(1)
	v_cvt_pk_bf16_f32 v20, v20, v21
	v_cvt_pk_bf16_f32 v21, v22, v23
	s_waitcnt lgkmcnt(0)
	v_cvt_pk_bf16_f32 v22, v36, v37
	v_mul_u32_u24_e32 v36, 0x1f8, v41
	v_add3_u32 v40, v40, v36, v45
	v_add_u32_e32 v45, s8, v45
	v_cvt_pk_bf16_f32 v23, v38, v39
	ds_read_b128 v[36:39], v40 offset:50688
	ds_read_b128 v[46:49], v40 offset:50704
	ds_read_b128 v[50:53], v45 offset:33792
	ds_read_b128 v[54:57], v45 offset:33808
	s_waitcnt lgkmcnt(1)
	v_mul_f32_e32 v58, v37, v51
	v_pk_fma_f32 v[58:59], v[36:37], v[50:51], v[58:59] op_sel_hi:[1,1,0] neg_lo:[0,0,1] neg_hi:[0,0,1]
	v_pk_mul_f32 v[36:37], v[36:37], v[50:51] op_sel:[0,1] op_sel_hi:[1,0]
	s_nop 0
	v_add_f32_e32 v36, v36, v37
	v_xor_b32_e32 v59, 0x80000000, v36
	v_mul_f32_e32 v36, v39, v53
	v_pk_fma_f32 v[50:51], v[38:39], v[52:53], v[36:37] op_sel_hi:[1,1,0] neg_lo:[0,0,1] neg_hi:[0,0,1]
	v_pk_mul_f32 v[36:37], v[38:39], v[52:53] op_sel:[0,1] op_sel_hi:[1,0]
	s_nop 0
	v_add_f32_e32 v36, v36, v37
	v_xor_b32_e32 v51, 0x80000000, v36
	s_waitcnt lgkmcnt(0)
	v_mul_f32_e32 v36, v47, v55
	v_pk_fma_f32 v[38:39], v[46:47], v[54:55], v[36:37] op_sel_hi:[1,1,0] neg_lo:[0,0,1] neg_hi:[0,0,1]
	v_pk_mul_f32 v[36:37], v[46:47], v[54:55] op_sel:[0,1] op_sel_hi:[1,0]
	s_nop 0
	v_add_f32_e32 v36, v36, v37
	v_xor_b32_e32 v39, 0x80000000, v36
	v_mul_f32_e32 v36, v49, v57
	v_pk_fma_f32 v[46:47], v[48:49], v[56:57], v[36:37] op_sel_hi:[1,1,0] neg_lo:[0,0,1] neg_hi:[0,0,1]
	v_pk_mul_f32 v[36:37], v[48:49], v[56:57] op_sel:[0,1] op_sel_hi:[1,0]
	v_cvt_pk_bf16_f32 v38, v38, v39
	v_add_f32_e32 v36, v36, v37
	v_xor_b32_e32 v47, 0x80000000, v36
	v_cvt_pk_bf16_f32 v36, v58, v59
	v_cvt_pk_bf16_f32 v37, v50, v51
	v_cvt_pk_bf16_f32 v39, v46, v47
	ds_read_b128 v[46:49], v40 offset:50816
	ds_read_b128 v[50:53], v40 offset:50832
	ds_read_b128 v[54:57], v45 offset:33920
	ds_read_b128 v[58:61], v45 offset:33936
	v_mfma_f32_16x16x32_bf16 v[36:39], v[36:39], v[32:35], 0
	s_waitcnt lgkmcnt(1)
	v_mul_f32_e32 v62, v47, v55
	v_pk_fma_f32 v[62:63], v[46:47], v[54:55], v[62:63] op_sel_hi:[1,1,0] neg_lo:[0,0,1] neg_hi:[0,0,1]
	v_pk_mul_f32 v[46:47], v[46:47], v[54:55] op_sel:[0,1] op_sel_hi:[1,0]
	s_nop 0
	v_add_f32_e32 v46, v46, v47
	v_xor_b32_e32 v63, 0x80000000, v46
	v_mul_f32_e32 v46, v49, v57
	v_pk_fma_f32 v[54:55], v[48:49], v[56:57], v[46:47] op_sel_hi:[1,1,0] neg_lo:[0,0,1] neg_hi:[0,0,1]
	v_pk_mul_f32 v[46:47], v[48:49], v[56:57] op_sel:[0,1] op_sel_hi:[1,0]
	s_nop 0
	v_add_f32_e32 v46, v46, v47
	v_xor_b32_e32 v55, 0x80000000, v46
	s_waitcnt lgkmcnt(0)
	v_mul_f32_e32 v46, v51, v59
	v_pk_fma_f32 v[48:49], v[50:51], v[58:59], v[46:47] op_sel_hi:[1,1,0] neg_lo:[0,0,1] neg_hi:[0,0,1]
	v_pk_mul_f32 v[46:47], v[50:51], v[58:59] op_sel:[0,1] op_sel_hi:[1,0]
	s_nop 0
	v_add_f32_e32 v46, v46, v47
	v_xor_b32_e32 v49, 0x80000000, v46
	v_mul_f32_e32 v46, v53, v61
	v_pk_fma_f32 v[50:51], v[52:53], v[60:61], v[46:47] op_sel_hi:[1,1,0] neg_lo:[0,0,1] neg_hi:[0,0,1]
	v_pk_mul_f32 v[46:47], v[52:53], v[60:61] op_sel:[0,1] op_sel_hi:[1,0]
	v_cvt_pk_bf16_f32 v48, v48, v49
	v_add_f32_e32 v46, v46, v47
	v_xor_b32_e32 v51, 0x80000000, v46
	v_cvt_pk_bf16_f32 v46, v62, v63
	v_cvt_pk_bf16_f32 v47, v54, v55
	v_cvt_pk_bf16_f32 v49, v50, v51
	s_nop 1
	v_mfma_f32_16x16x32_bf16 v[36:39], v[46:49], v[28:31], v[36:39]
	ds_read_b128 v[46:49], v40 offset:50944
	ds_read_b128 v[50:53], v40 offset:50960
	ds_read_b128 v[54:57], v45 offset:34048
	ds_read_b128 v[58:61], v45 offset:34064
	s_waitcnt lgkmcnt(1)
	v_mul_f32_e32 v62, v47, v55
	v_pk_fma_f32 v[62:63], v[46:47], v[54:55], v[62:63] op_sel_hi:[1,1,0] neg_lo:[0,0,1] neg_hi:[0,0,1]
	v_pk_mul_f32 v[46:47], v[46:47], v[54:55] op_sel:[0,1] op_sel_hi:[1,0]
	s_nop 0
	v_add_f32_e32 v46, v46, v47
	v_xor_b32_e32 v63, 0x80000000, v46
	v_mul_f32_e32 v46, v49, v57
	v_pk_fma_f32 v[54:55], v[48:49], v[56:57], v[46:47] op_sel_hi:[1,1,0] neg_lo:[0,0,1] neg_hi:[0,0,1]
	v_pk_mul_f32 v[46:47], v[48:49], v[56:57] op_sel:[0,1] op_sel_hi:[1,0]
	s_nop 0
	v_add_f32_e32 v46, v46, v47
	v_xor_b32_e32 v55, 0x80000000, v46
	s_waitcnt lgkmcnt(0)
; __device__ __forceinline__ unsigned f2bf(float f) { unsigned u = __builtin_bit_cast(unsigned, f); return (u + 0x7fffu + ((u >> 16) & 1u)) >> 16; }
; __device__ __forceinline__ unsigned pk2(float lo, float hi) { const f32x2 v = {lo, hi}; const bf16x2_n b = __builtin_convertvector(v, bf16x2_n); return __builtin_bit_cast(unsigned, b); }
; __device__ __forceinline__ f32x4 mfma16(bf16x8 a, bf16x8 b, f32x4 c) { return __builtin_amdgcn_mfma_f32_16x16x32_bf16(a, b, c, 0, 0, 0); }
; __device__ __forceinline__ void s5_phase(LAS unsigned char* lds, const bf16* PROJ, const float* a_re, const float* a_im, const float* b_re, const float* b_im, const float* c_re, const float* c_im, ...
;     ...
; #pragma unroll
;             for (int ts = 0; ts < 2; ++ts) { const int tau = ts ? 15 - w : w; f32x4 acc = (f32x4){0.f, 0.f, 0.f, 0.f};
; #pragma unroll
;                 for (int ks = 0; ks < 4; ++ks) { float v[8];
; #pragma unroll
;                     for (int pp = 0; pp < 4; ++pp) { const int p = 16 * ks + 4 * q4 + pp; const f32x2 cc = CC[l15 * 64 + p], pw = POW[tau * 64 + p];
;                         v[2 * pp] = cc.x * pw.x - cc.y * pw.y; v[2 * pp + 1] = -(cc.x * pw.y + cc.y * pw.x); }
;                     v4u pk; pk.x = pk2(v[0], v[1]); pk.y = pk2(v[2], v[3]); pk.z = pk2(v[4], v[5]); pk.w = pk2(v[6], v[7]);
;                     acc = mfma16(__builtin_bit_cast(bf16x8, pk), bfK[ks], acc); asm volatile("" ::: "memory"); }
; #pragma unroll
;                 for (int r = 0; r < 4; ++r) { const int c = 4 * q4 + r; float kv = acc[r]; if (tau == 0 && c == l15) kv += dvec[g * 16 + c];
;                     KTAB[(tau * 16 + c) * 16 + l15] = (unsigned short)f2bf(kv); } }
	v_mul_f32_e32 v46, v51, v59
	v_pk_fma_f32 v[48:49], v[50:51], v[58:59], v[46:47] op_sel_hi:[1,1,0] neg_lo:[0,0,1] neg_hi:[0,0,1]
	v_pk_mul_f32 v[46:47], v[50:51], v[58:59] op_sel:[0,1] op_sel_hi:[1,0]
	s_nop 0
	v_add_f32_e32 v46, v46, v47
	v_xor_b32_e32 v49, 0x80000000, v46
	v_mul_f32_e32 v46, v53, v61
	v_pk_fma_f32 v[50:51], v[52:53], v[60:61], v[46:47] op_sel_hi:[1,1,0] neg_lo:[0,0,1] neg_hi:[0,0,1]
	v_pk_mul_f32 v[46:47], v[52:53], v[60:61] op_sel:[0,1] op_sel_hi:[1,0]
	v_cvt_pk_bf16_f32 v48, v48, v49
	v_add_f32_e32 v46, v46, v47
	v_xor_b32_e32 v51, 0x80000000, v46
	v_cvt_pk_bf16_f32 v46, v62, v63
	v_cvt_pk_bf16_f32 v47, v54, v55
	v_cvt_pk_bf16_f32 v49, v50, v51
	s_nop 1
	v_mfma_f32_16x16x32_bf16 v[36:39], v[46:49], v[24:27], v[36:39]
	ds_read_b128 v[46:49], v40 offset:51072
	ds_read_b128 v[50:53], v40 offset:51088
	ds_read_b128 v[54:57], v45 offset:34176
	ds_read_b128 v[58:61], v45 offset:34192
	s_waitcnt lgkmcnt(1)
	v_mul_f32_e32 v62, v47, v55
	v_pk_fma_f32 v[62:63], v[46:47], v[54:55], v[62:63] op_sel_hi:[1,1,0] neg_lo:[0,0,1] neg_hi:[0,0,1]
	v_pk_mul_f32 v[46:47], v[46:47], v[54:55] op_sel:[0,1] op_sel_hi:[1,0]
	s_nop 0
	v_add_f32_e32 v45, v46, v47
	v_mul_f32_e32 v46, v49, v57
	v_pk_fma_f32 v[54:55], v[48:49], v[56:57], v[46:47] op_sel_hi:[1,1,0] neg_lo:[0,0,1] neg_hi:[0,0,1]
	v_pk_mul_f32 v[46:47], v[48:49], v[56:57] op_sel:[0,1] op_sel_hi:[1,0]
	v_xor_b32_e32 v45, 0x80000000, v45
	v_add_f32_e32 v46, v46, v47
	v_xor_b32_e32 v55, 0x80000000, v46
	s_waitcnt lgkmcnt(0)
	v_mul_f32_e32 v46, v51, v59
	v_pk_fma_f32 v[48:49], v[50:51], v[58:59], v[46:47] op_sel_hi:[1,1,0] neg_lo:[0,0,1] neg_hi:[0,0,1]
	v_pk_mul_f32 v[46:47], v[50:51], v[58:59] op_sel:[0,1] op_sel_hi:[1,0]
	s_nop 0
	v_add_f32_e32 v46, v46, v47
	v_xor_b32_e32 v49, 0x80000000, v46
	v_mul_f32_e32 v46, v53, v61
	v_pk_fma_f32 v[50:51], v[52:53], v[60:61], v[46:47] op_sel_hi:[1,1,0] neg_lo:[0,0,1] neg_hi:[0,0,1]
	v_pk_mul_f32 v[46:47], v[52:53], v[60:61] op_sel:[0,1] op_sel_hi:[1,0]
	v_cvt_pk_bf16_f32 v48, v48, v49
	v_add_f32_e32 v46, v46, v47
	v_xor_b32_e32 v51, 0x80000000, v46
	v_cvt_pk_bf16_f32 v46, v62, v45
	v_cvt_pk_bf16_f32 v47, v54, v55
	v_cvt_pk_bf16_f32 v49, v50, v51
	v_or_b32_e32 v45, s1, v41
	v_lshlrev_b32_e32 v45, 2, v45
	global_load_dword v247, v45, s[62:63]
	v_mfma_f32_16x16x32_bf16 v[36:39], v[46:49], v[20:23], v[36:39]
	s_and_saveexec_b64 s[8:9], s[26:27]
	s_cbranch_execz .LBB0_1556
	s_nop 0
	s_waitcnt vmcnt(0)
	s_nop 3
	v_add_f32_e32 v36, v36, v247
.LBB0_1556:
	s_or_b64 exec, exec, s[8:9]
	v_lshl_add_u32 v46, v41, 1, s23
	v_readlane_b32 s8, v255, 13
	v_bfe_u32 v48, v36, 16, 1
	v_cmp_eq_u32_e64 s[42:43], v44, v41
	v_add_u32_e32 v47, s8, v46
	s_movk_i32 s8, 0x7fff
	v_add3_u32 v48, v36, v48, s8
	v_lshlrev_b32_e32 v36, 5, v0
	v_add_u32_e32 v49, v47, v36
	s_and_b64 s[26:27], s[68:69], s[42:43]
	ds_write_b16_d16_hi v49, v48
	s_and_saveexec_b64 s[8:9], s[26:27]
	s_cbranch_execz .LBB0_1558
	s_nop 0
	s_waitcnt vmcnt(0)
	v_add_f32_e32 v37, v37, v247
.LBB0_1558:
	s_or_b64 exec, exec, s[8:9]
	v_bfe_u32 v48, v37, 16, 1
	s_movk_i32 s8, 0x7fff
	v_add3_u32 v48, v37, v48, s8
	v_lshlrev_b32_e32 v37, 5, v44
	v_cmp_eq_u32_e64 s[44:45], v43, v41
	v_add_u32_e32 v44, v47, v37
	s_and_b64 s[26:27], s[68:69], s[44:45]
	ds_write_b16_d16_hi v44, v48
	s_and_saveexec_b64 s[8:9], s[26:27]
	s_cbranch_execz .LBB0_1560
	s_nop 0
	s_waitcnt vmcnt(0)
	v_add_f32_e32 v38, v38, v247
.LBB0_1560:
	s_or_b64 exec, exec, s[8:9]
	v_bfe_u32 v44, v38, 16, 1
	s_movk_i32 s8, 0x7fff
	v_add3_u32 v44, v38, v44, s8
	v_lshlrev_b32_e32 v38, 5, v43
	v_cmp_eq_u32_e64 s[46:47], v42, v41
	v_add_u32_e32 v43, v47, v38
	s_and_b64 s[26:27], s[68:69], s[46:47]
	ds_write_b16_d16_hi v43, v44
	s_and_saveexec_b64 s[8:9], s[26:27]
	s_cbranch_execz .LBB0_1562
	s_nop 0
	s_waitcnt vmcnt(0)
	v_add_f32_e32 v39, v39, v247
.LBB0_1562:
	s_or_b64 exec, exec, s[8:9]
	v_bfe_u32 v41, v39, 16, 1
	s_movk_i32 s8, 0x7fff
	v_add3_u32 v41, v39, v41, s8
	v_lshlrev_b32_e32 v39, 5, v42
	v_add_u32_e32 v42, v47, v39
	v_readlane_b32 s8, v255, 10
	ds_write_b16_d16_hi v42, v41
	s_and_b64 s[26:27], s[70:71], vcc
	v_lshl_add_u32 v41, v0, 3, s8
	ds_read_b128 v[48:51], v41 offset:33792
	ds_read_b128 v[52:55], v40 offset:50688
	ds_read_b128 v[56:59], v40 offset:50704
	ds_read_b128 v[60:63], v41 offset:33808
	s_waitcnt lgkmcnt(2)
	v_mul_f32_e32 v0, v53, v49
	v_pk_fma_f32 v[42:43], v[52:53], v[48:49], v[0:1] op_sel_hi:[1,1,0] neg_lo:[0,0,1] neg_hi:[0,0,1]
	v_pk_mul_f32 v[48:49], v[52:53], v[48:49] op_sel:[0,1] op_sel_hi:[1,0]
	s_nop 0
	v_add_f32_e32 v0, v48, v49
	v_xor_b32_e32 v43, 0x80000000, v0
	v_mul_f32_e32 v0, v55, v51
	v_pk_mul_f32 v[48:49], v[54:55], v[50:51] op_sel:[0,1] op_sel_hi:[1,0]
	v_pk_fma_f32 v[52:53], v[54:55], v[50:51], v[0:1] op_sel_hi:[1,1,0] neg_lo:[0,0,1] neg_hi:[0,0,1]
	v_add_f32_e32 v0, v48, v49
	v_xor_b32_e32 v44, 0x80000000, v0
	s_waitcnt lgkmcnt(0)
	v_mul_f32_e32 v0, v57, v61
	v_pk_mul_f32 v[48:49], v[56:57], v[60:61] op_sel:[0,1] op_sel_hi:[1,0]
	v_pk_fma_f32 v[50:51], v[56:57], v[60:61], v[0:1] op_sel_hi:[1,1,0] neg_lo:[0,0,1] neg_hi:[0,0,1]
	v_add_f32_e32 v0, v48, v49
	v_xor_b32_e32 v47, 0x80000000, v0
	v_mul_f32_e32 v0, v59, v63
	v_pk_mul_f32 v[48:49], v[58:59], v[62:63] op_sel:[0,1] op_sel_hi:[1,0]
	v_pk_fma_f32 v[54:55], v[58:59], v[62:63], v[0:1] op_sel_hi:[1,1,0] neg_lo:[0,0,1] neg_hi:[0,0,1]
	v_add_f32_e32 v0, v48, v49
	v_xor_b32_e32 v0, 0x80000000, v0
	v_cvt_pk_bf16_f32 v49, v52, v44
	v_cvt_pk_bf16_f32 v51, v54, v0
	ds_read_b128 v[52:55], v40 offset:50816
	ds_read_b128 v[56:59], v41 offset:33920
	v_cvt_pk_bf16_f32 v48, v42, v43
	v_cvt_pk_bf16_f32 v50, v50, v47
	s_waitcnt lgkmcnt(0)
; __device__ __forceinline__ unsigned f2bf(float f) { unsigned u = __builtin_bit_cast(unsigned, f); return (u + 0x7fffu + ((u >> 16) & 1u)) >> 16; }
; __device__ __forceinline__ unsigned pk2(float lo, float hi) { const f32x2 v = {lo, hi}; const bf16x2_n b = __builtin_convertvector(v, bf16x2_n); return __builtin_bit_cast(unsigned, b); }
; __device__ __forceinline__ f32x4 mfma16(bf16x8 a, bf16x8 b, f32x4 c) { return __builtin_amdgcn_mfma_f32_16x16x32_bf16(a, b, c, 0, 0, 0); }
; __device__ __forceinline__ void s5_phase(LAS unsigned char* lds, const bf16* PROJ, const float* a_re, const float* a_im, const float* b_re, const float* b_im, const float* c_re, const float* c_im, ...
;     ...
; #pragma unroll
;             for (int ts = 0; ts < 2; ++ts) { const int tau = ts ? 15 - w : w; f32x4 acc = (f32x4){0.f, 0.f, 0.f, 0.f};
; #pragma unroll
;                 for (int ks = 0; ks < 4; ++ks) { float v[8];
; #pragma unroll
;                     for (int pp = 0; pp < 4; ++pp) { const int p = 16 * ks + 4 * q4 + pp; const f32x2 cc = CC[l15 * 64 + p], pw = POW[tau * 64 + p];
;                         v[2 * pp] = cc.x * pw.x - cc.y * pw.y; v[2 * pp + 1] = -(cc.x * pw.y + cc.y * pw.x); }
;                     v4u pk; pk.x = pk2(v[0], v[1]); pk.y = pk2(v[2], v[3]); pk.z = pk2(v[4], v[5]); pk.w = pk2(v[6], v[7]);
;                     acc = mfma16(__builtin_bit_cast(bf16x8, pk), bfK[ks], acc); asm volatile("" ::: "memory"); }
; #pragma unroll
;                 for (int r = 0; r < 4; ++r) { const int c = 4 * q4 + r; float kv = acc[r]; if (tau == 0 && c == l15) kv += dvec[g * 16 + c];
;                     KTAB[(tau * 16 + c) * 16 + l15] = (unsigned short)f2bf(kv); } }
	v_mul_f32_e32 v0, v53, v57
	v_mfma_f32_16x16x32_bf16 v[32:35], v[48:51], v[32:35], 0
	ds_read_b128 v[48:51], v40 offset:50832
	ds_read_b128 v[60:63], v41 offset:33936
	v_pk_fma_f32 v[42:43], v[52:53], v[56:57], v[0:1] op_sel_hi:[1,1,0] neg_lo:[0,0,1] neg_hi:[0,0,1]
	v_pk_mul_f32 v[52:53], v[52:53], v[56:57] op_sel:[0,1] op_sel_hi:[1,0]
	s_nop 0
	v_add_f32_e32 v0, v52, v53
	v_xor_b32_e32 v43, 0x80000000, v0
	v_mul_f32_e32 v0, v55, v59
	v_pk_fma_f32 v[52:53], v[54:55], v[58:59], v[0:1] op_sel_hi:[1,1,0] neg_lo:[0,0,1] neg_hi:[0,0,1]
	v_pk_mul_f32 v[54:55], v[54:55], v[58:59] op_sel:[0,1] op_sel_hi:[1,0]
	s_nop 0
	v_add_f32_e32 v0, v54, v55
	v_xor_b32_e32 v44, 0x80000000, v0
	s_waitcnt lgkmcnt(0)
	v_mul_f32_e32 v0, v49, v61
	v_pk_fma_f32 v[54:55], v[48:49], v[60:61], v[0:1] op_sel_hi:[1,1,0] neg_lo:[0,0,1] neg_hi:[0,0,1]
	v_pk_mul_f32 v[48:49], v[48:49], v[60:61] op_sel:[0,1] op_sel_hi:[1,0]
	s_nop 0
	v_add_f32_e32 v0, v48, v49
	v_xor_b32_e32 v47, 0x80000000, v0
	v_mul_f32_e32 v0, v51, v63
	v_pk_mul_f32 v[48:49], v[50:51], v[62:63] op_sel:[0,1] op_sel_hi:[1,0]
	v_pk_fma_f32 v[56:57], v[50:51], v[62:63], v[0:1] op_sel_hi:[1,1,0] neg_lo:[0,0,1] neg_hi:[0,0,1]
	v_add_f32_e32 v0, v48, v49
	v_xor_b32_e32 v0, 0x80000000, v0
	v_cvt_pk_bf16_f32 v49, v52, v44
	v_cvt_pk_bf16_f32 v50, v54, v47
	v_cvt_pk_bf16_f32 v51, v56, v0
	ds_read_b128 v[52:55], v40 offset:50944
	ds_read_b128 v[56:59], v41 offset:34048
	v_cvt_pk_bf16_f32 v48, v42, v43
	s_waitcnt lgkmcnt(0)
	v_mul_f32_e32 v0, v53, v57
	v_mfma_f32_16x16x32_bf16 v[28:31], v[48:51], v[28:31], v[32:35]
	s_nop 2
	ds_read_b128 v[32:35], v40 offset:50960
	ds_read_b128 v[48:51], v41 offset:34064
	v_pk_fma_f32 v[42:43], v[52:53], v[56:57], v[0:1] op_sel_hi:[1,1,0] neg_lo:[0,0,1] neg_hi:[0,0,1]
	v_pk_mul_f32 v[52:53], v[52:53], v[56:57] op_sel:[0,1] op_sel_hi:[1,0]
	s_nop 0
	v_add_f32_e32 v0, v52, v53
	v_xor_b32_e32 v43, 0x80000000, v0
	v_mul_f32_e32 v0, v55, v59
	v_pk_fma_f32 v[52:53], v[54:55], v[58:59], v[0:1] op_sel_hi:[1,1,0] neg_lo:[0,0,1] neg_hi:[0,0,1]
	v_pk_mul_f32 v[54:55], v[54:55], v[58:59] op_sel:[0,1] op_sel_hi:[1,0]
	s_nop 0
	v_add_f32_e32 v0, v54, v55
	v_xor_b32_e32 v44, 0x80000000, v0
	s_waitcnt lgkmcnt(0)
	v_mul_f32_e32 v0, v33, v49
	v_pk_fma_f32 v[54:55], v[32:33], v[48:49], v[0:1] op_sel_hi:[1,1,0] neg_lo:[0,0,1] neg_hi:[0,0,1]
	v_pk_mul_f32 v[32:33], v[32:33], v[48:49] op_sel:[0,1] op_sel_hi:[1,0]
	s_nop 0
	v_add_f32_e32 v0, v32, v33
	v_xor_b32_e32 v47, 0x80000000, v0
	v_mul_f32_e32 v0, v35, v51
	v_pk_mul_f32 v[32:33], v[34:35], v[50:51] op_sel:[0,1] op_sel_hi:[1,0]
	v_pk_fma_f32 v[48:49], v[34:35], v[50:51], v[0:1] op_sel_hi:[1,1,0] neg_lo:[0,0,1] neg_hi:[0,0,1]
	v_add_f32_e32 v0, v32, v33
	v_xor_b32_e32 v0, 0x80000000, v0
	v_cvt_pk_bf16_f32 v32, v42, v43
	v_cvt_pk_bf16_f32 v33, v52, v44
	v_cvt_pk_bf16_f32 v34, v54, v47
	v_cvt_pk_bf16_f32 v35, v48, v0
	ds_read_b128 v[48:51], v40 offset:51072
	ds_read_b128 v[52:55], v41 offset:34176
	v_mfma_f32_16x16x32_bf16 v[24:27], v[32:35], v[24:27], v[28:31]
	s_nop 2
	ds_read_b128 v[28:31], v40 offset:51088
	ds_read_b128 v[32:35], v41 offset:34192
	s_waitcnt lgkmcnt(2)
	v_mul_f32_e32 v0, v49, v53
	v_pk_mul_f32 v[42:43], v[48:49], v[52:53] op_sel:[0,1] op_sel_hi:[1,0]
	v_pk_fma_f32 v[40:41], v[48:49], v[52:53], v[0:1] op_sel_hi:[1,1,0] neg_lo:[0,0,1] neg_hi:[0,0,1]
	v_add_f32_e32 v0, v42, v43
	v_xor_b32_e32 v41, 0x80000000, v0
	v_mul_f32_e32 v0, v51, v55
	v_pk_mul_f32 v[48:49], v[50:51], v[54:55] op_sel:[0,1] op_sel_hi:[1,0]
	v_pk_fma_f32 v[42:43], v[50:51], v[54:55], v[0:1] op_sel_hi:[1,1,0] neg_lo:[0,0,1] neg_hi:[0,0,1]
	v_add_f32_e32 v0, v48, v49
	v_xor_b32_e32 v43, 0x80000000, v0
	s_waitcnt lgkmcnt(0)
	v_mul_f32_e32 v0, v29, v33
	v_pk_fma_f32 v[48:49], v[28:29], v[32:33], v[0:1] op_sel_hi:[1,1,0] neg_lo:[0,0,1] neg_hi:[0,0,1]
	v_pk_mul_f32 v[28:29], v[28:29], v[32:33] op_sel:[0,1] op_sel_hi:[1,0]
	s_nop 0
	v_add_f32_e32 v0, v28, v29
	v_xor_b32_e32 v44, 0x80000000, v0
	v_mul_f32_e32 v0, v31, v35
	v_pk_mul_f32 v[28:29], v[30:31], v[34:35] op_sel:[0,1] op_sel_hi:[1,0]
	v_pk_fma_f32 v[32:33], v[30:31], v[34:35], v[0:1] op_sel_hi:[1,1,0] neg_lo:[0,0,1] neg_hi:[0,0,1]
	v_add_f32_e32 v0, v28, v29
	v_xor_b32_e32 v0, 0x80000000, v0
	v_cvt_pk_bf16_f32 v28, v40, v41
	v_cvt_pk_bf16_f32 v29, v42, v43
	v_cvt_pk_bf16_f32 v30, v48, v44
	v_cvt_pk_bf16_f32 v31, v32, v0
	s_nop 1
	v_mfma_f32_16x16x32_bf16 v[20:23], v[28:31], v[20:23], v[24:27]
	s_and_saveexec_b64 s[8:9], s[26:27]
	s_cbranch_execz .LBB0_1564
	s_nop 0
	s_waitcnt vmcnt(0)
	s_nop 3
	v_add_f32_e32 v20, v20, v247
.LBB0_1564:
	s_or_b64 exec, exec, s[8:9]
	v_readlane_b32 s8, v255, 14
	s_nop 3
	v_bfe_u32 v24, v20, 16, 1
	s_and_b64 s[26:27], s[70:71], s[42:43]
	v_add_u32_e32 v0, s8, v46
	s_movk_i32 s8, 0x7fff
	v_add3_u32 v20, v20, v24, s8
	v_add_u32_e32 v24, v0, v36
	ds_write_b16_d16_hi v24, v20
	s_and_saveexec_b64 s[8:9], s[26:27]
	s_cbranch_execz .LBB0_1566
	s_nop 0
	s_waitcnt vmcnt(0)
	v_add_f32_e32 v21, v21, v247
.LBB0_1566:
	s_or_b64 exec, exec, s[8:9]
	v_bfe_u32 v20, v21, 16, 1
	s_movk_i32 s8, 0x7fff
	v_add3_u32 v20, v21, v20, s8
	v_add_u32_e32 v21, v0, v37
	s_and_b64 s[26:27], s[70:71], s[44:45]
	ds_write_b16_d16_hi v21, v20
	s_and_saveexec_b64 s[8:9], s[26:27]
	s_cbranch_execz .LBB0_1568
	s_nop 0
	s_waitcnt vmcnt(0)
	v_add_f32_e32 v22, v22, v247
.LBB0_1568:
	s_or_b64 exec, exec, s[8:9]
	v_bfe_u32 v20, v22, 16, 1
	s_movk_i32 s8, 0x7fff
	v_add3_u32 v20, v22, v20, s8
	v_add_u32_e32 v21, v0, v38
	s_and_b64 s[26:27], s[70:71], s[46:47]
	ds_write_b16_d16_hi v21, v20
	s_and_saveexec_b64 s[8:9], s[26:27]
	s_cbranch_execz .LBB0_1570
	s_nop 0
	s_waitcnt vmcnt(0)
	v_add_f32_e32 v23, v23, v247
